# P4 set-up: per-head bias-table max scan keeps 4 LDS reads in flight instead of waiting after each (prologue de-serialisation)
# speedup vs baseline: 1.0097x; 1.0097x over previous
; #define LAS __attribute__((address_space(3)))
; __device__ __forceinline__ void phase4(const Params& p, LAS unsigned char* lds, int tid, int lane, int wave) {
;     ...
;     if (wave == 0) { const float* qg = p.in[13]; const float* kg = p.in[14]; LAS float* pm = (LAS float*)(lds + MISC4_OFF + 2304); const LAS float* lut = (const LAS float*)(lds + LUT_OFF);
;         float a = fabsf(qg[lane]), b1 = fabsf(kg[64 + lane]), b2 = fabsf(kg[128 + lane]);
; #pragma unroll
;         for (int o = 1; o < 64; o <<= 1) { a = fmaxf(a, __shfl_xor(a, o)); b1 = fmaxf(b1, __shfl_xor(b1, o)); b2 = fmaxf(b2, __shfl_xor(b2, o)); }
;         float bm = -1.0e30f, ball = 0.f;
;         if (lane < 8) {
.LBB0_451:
	s_or_b64 exec, exec, s[2:3]
	v_readlane_b32 s2, v251, 36
	v_readlane_b32 s3, v251, 37
	s_and_b64 vcc, exec, s[2:3]
	s_cbranch_vccz .LBB0_457
	global_load_dword v4, v[172:173], off
	global_load_dword v6, v[174:175], off offset:256
	global_load_dword v8, v[174:175], off offset:512
	v_and_b32_e32 v2, 64, v194
	v_add_u32_e32 v11, 64, v2
	v_xor_b32_e32 v2, 1, v194
	v_cmp_lt_i32_e32 vcc, v2, v11
	v_mov_b32_e32 v15, 0xf149f2ca
	s_waitcnt vmcnt(2)
	v_and_b32_e32 v5, 0x7fffffff, v4
	v_cndmask_b32_e32 v2, v194, v2, vcc
	v_lshlrev_b32_e32 v2, 2, v2
	ds_bpermute_b32 v5, v2, v5
	s_waitcnt vmcnt(1)
	v_and_b32_e32 v7, 0x7fffffff, v6
	v_max_f32_e64 v4, |v4|, |v4|
	s_waitcnt vmcnt(0)
	v_and_b32_e32 v9, 0x7fffffff, v8
	v_max_f32_e64 v6, |v6|, |v6|
	s_waitcnt lgkmcnt(0)
	v_max_f32_e32 v5, v5, v5
	v_max_f32_e32 v5, v4, v5
	ds_bpermute_b32 v4, v2, v7
	v_max_f32_e64 v7, |v8|, |v8|
	s_waitcnt lgkmcnt(0)
	v_max_f32_e32 v4, v4, v4
	v_max_f32_e32 v6, v6, v4
	ds_bpermute_b32 v4, v2, v9
	s_waitcnt lgkmcnt(0)
	v_max_f32_e32 v4, v4, v4
	v_max_f32_e32 v7, v7, v4
	v_xor_b32_e32 v4, 2, v194
	v_cmp_lt_i32_e32 vcc, v4, v11
	s_nop 1
	v_cndmask_b32_e32 v4, v194, v4, vcc
	v_lshlrev_b32_e32 v4, 2, v4
	ds_bpermute_b32 v8, v4, v5
	s_waitcnt lgkmcnt(0)
	v_max_f32_e32 v8, v8, v8
	v_max_f32_e32 v8, v5, v8
	ds_bpermute_b32 v5, v4, v6
	s_waitcnt lgkmcnt(0)
	v_max_f32_e32 v5, v5, v5
	v_max_f32_e32 v6, v6, v5
	ds_bpermute_b32 v5, v4, v7
	s_waitcnt lgkmcnt(0)
	v_max_f32_e32 v5, v5, v5
	v_max_f32_e32 v7, v7, v5
	v_xor_b32_e32 v5, 4, v194
	v_cmp_lt_i32_e32 vcc, v5, v11
	s_nop 1
	v_cndmask_b32_e32 v5, v194, v5, vcc
	v_lshlrev_b32_e32 v5, 2, v5
	ds_bpermute_b32 v9, v5, v8
	s_waitcnt lgkmcnt(0)
	v_max_f32_e32 v9, v9, v9
	v_max_f32_e32 v8, v8, v9
	ds_bpermute_b32 v9, v5, v6
	s_waitcnt lgkmcnt(0)
	v_max_f32_e32 v9, v9, v9
	v_max_f32_e32 v9, v6, v9
	ds_bpermute_b32 v6, v5, v7
	s_waitcnt lgkmcnt(0)
	v_max_f32_e32 v6, v6, v6
	v_max_f32_e32 v7, v7, v6
	v_xor_b32_e32 v6, 8, v194
	v_cmp_lt_i32_e32 vcc, v6, v11
	s_nop 1
	v_cndmask_b32_e32 v6, v194, v6, vcc
	v_lshlrev_b32_e32 v6, 2, v6
	ds_bpermute_b32 v10, v6, v8
	s_waitcnt lgkmcnt(0)
	v_max_f32_e32 v10, v10, v10
	v_max_f32_e32 v8, v8, v10
	ds_bpermute_b32 v10, v6, v9
	s_waitcnt lgkmcnt(0)
	v_max_f32_e32 v10, v10, v10
	v_max_f32_e32 v9, v9, v10
	ds_bpermute_b32 v10, v6, v7
	s_waitcnt lgkmcnt(0)
	v_max_f32_e32 v10, v10, v10
	v_max_f32_e32 v12, v7, v10
	v_xor_b32_e32 v7, 16, v194
	v_cmp_lt_i32_e32 vcc, v7, v11
	s_nop 1
	v_cndmask_b32_e32 v7, v194, v7, vcc
	v_lshlrev_b32_e32 v10, 2, v7
	ds_bpermute_b32 v7, v10, v8
	s_waitcnt lgkmcnt(0)
	v_max_f32_e32 v7, v7, v7
	v_max_f32_e32 v7, v8, v7
	ds_bpermute_b32 v8, v10, v9
	s_waitcnt lgkmcnt(0)
	v_max_f32_e32 v8, v8, v8
	v_max_f32_e32 v8, v9, v8
	ds_bpermute_b32 v9, v10, v12
	s_waitcnt lgkmcnt(0)
	v_max_f32_e32 v9, v9, v9
	v_max_f32_e32 v9, v12, v9
	v_xor_b32_e32 v12, 32, v194
	v_cmp_lt_i32_e32 vcc, v12, v11
	s_nop 1
	v_cndmask_b32_e32 v11, v194, v12, vcc
	v_lshlrev_b32_e32 v11, 2, v11
	ds_bpermute_b32 v14, v11, v7
	ds_bpermute_b32 v13, v11, v8
	ds_bpermute_b32 v12, v11, v9
	s_mov_b64 s[2:3], exec
	v_readlane_b32 s4, v251, 38
	v_readlane_b32 s5, v251, 39
	s_and_b64 s[4:5], s[2:3], s[4:5]
	s_mov_b64 exec, s[4:5]
	s_cbranch_execz .LBB0_454
; __device__ __forceinline__ void phase4(const Params& p, LAS unsigned char* lds, int tid, int lane, int wave) {
;     ...
;         if (lane < 8) {
;             for (int d = 0; d < 128; ++d) bm = fmaxf(bm, lut[lane * 128 + d]);
;             pm[8 + lane] = bm; }
	ds_read_b128 v[16:19], v167
	ds_read_b128 v[20:23], v167 offset:16
	ds_read_b128 v[24:27], v167 offset:32
	ds_read_b128 v[28:31], v167 offset:48
	s_waitcnt lgkmcnt(3)
	v_max3_f32 v15, v16, s94, v17
	v_max3_f32 v15, v15, v18, v19
	ds_read_b128 v[16:19], v167 offset:64
	s_waitcnt lgkmcnt(3)
	v_max3_f32 v15, v15, v20, v21
	v_max3_f32 v15, v15, v22, v23
	ds_read_b128 v[20:23], v167 offset:80
	s_waitcnt lgkmcnt(3)
	v_max3_f32 v15, v15, v24, v25
	v_max3_f32 v15, v15, v26, v27
	ds_read_b128 v[24:27], v167 offset:96
	s_waitcnt lgkmcnt(3)
	v_max3_f32 v15, v15, v28, v29
	v_max3_f32 v15, v15, v30, v31
	ds_read_b128 v[28:31], v167 offset:112
	s_waitcnt lgkmcnt(3)
	v_max3_f32 v15, v15, v16, v17
	v_max3_f32 v15, v15, v18, v19
	ds_read_b128 v[16:19], v167 offset:128
	s_waitcnt lgkmcnt(3)
	v_max3_f32 v15, v15, v20, v21
	v_max3_f32 v15, v15, v22, v23
	ds_read_b128 v[20:23], v167 offset:144
	s_waitcnt lgkmcnt(3)
	v_max3_f32 v15, v15, v24, v25
	v_max3_f32 v15, v15, v26, v27
	ds_read_b128 v[24:27], v167 offset:160
	s_waitcnt lgkmcnt(3)
	v_max3_f32 v15, v15, v28, v29
	v_max3_f32 v15, v15, v30, v31
	ds_read_b128 v[28:31], v167 offset:176
	s_waitcnt lgkmcnt(3)
	v_max3_f32 v15, v15, v16, v17
	v_max3_f32 v15, v15, v18, v19
	ds_read_b128 v[16:19], v167 offset:192
	s_waitcnt lgkmcnt(3)
	v_max3_f32 v15, v15, v20, v21
	v_max3_f32 v15, v15, v22, v23
	ds_read_b128 v[20:23], v167 offset:208
	s_waitcnt lgkmcnt(3)
	v_max3_f32 v15, v15, v24, v25
	v_max3_f32 v15, v15, v26, v27
	ds_read_b128 v[24:27], v167 offset:224
	s_waitcnt lgkmcnt(3)
	v_max3_f32 v15, v15, v28, v29
	v_max3_f32 v15, v15, v30, v31
	ds_read_b128 v[28:31], v167 offset:240
	s_waitcnt lgkmcnt(3)
	v_max3_f32 v15, v15, v16, v17
	v_max3_f32 v15, v15, v18, v19
	ds_read_b128 v[16:19], v167 offset:256
	s_waitcnt lgkmcnt(3)
	v_max3_f32 v15, v15, v20, v21
	v_max3_f32 v15, v15, v22, v23
	ds_read_b128 v[20:23], v167 offset:272
	s_waitcnt lgkmcnt(3)
	v_max3_f32 v15, v15, v24, v25
	v_max3_f32 v15, v15, v26, v27
	ds_read_b128 v[24:27], v167 offset:288
	s_waitcnt lgkmcnt(3)
	v_max3_f32 v15, v15, v28, v29
	v_max3_f32 v15, v15, v30, v31
	ds_read_b128 v[28:31], v167 offset:304
	s_waitcnt lgkmcnt(3)
	v_max3_f32 v15, v15, v16, v17
	v_max3_f32 v15, v15, v18, v19
	ds_read_b128 v[16:19], v167 offset:320
	s_waitcnt lgkmcnt(3)
	v_max3_f32 v15, v15, v20, v21
	v_max3_f32 v15, v15, v22, v23
	ds_read_b128 v[20:23], v167 offset:336
	s_waitcnt lgkmcnt(3)
	v_max3_f32 v15, v15, v24, v25
	v_max3_f32 v15, v15, v26, v27
	ds_read_b128 v[24:27], v167 offset:352
	s_waitcnt lgkmcnt(3)
	v_max3_f32 v15, v15, v28, v29
	v_max3_f32 v15, v15, v30, v31
	ds_read_b128 v[28:31], v167 offset:368
	s_waitcnt lgkmcnt(3)
	v_max3_f32 v15, v15, v16, v17
	v_max3_f32 v15, v15, v18, v19
	ds_read_b128 v[16:19], v167 offset:384
	s_waitcnt lgkmcnt(3)
	v_max3_f32 v15, v15, v20, v21
	v_max3_f32 v15, v15, v22, v23
	ds_read_b128 v[20:23], v167 offset:400
	s_waitcnt lgkmcnt(3)
	v_max3_f32 v15, v15, v24, v25
	v_max3_f32 v15, v15, v26, v27
	ds_read_b128 v[24:27], v167 offset:416
	s_waitcnt lgkmcnt(3)
	v_max3_f32 v15, v15, v28, v29
	v_max3_f32 v15, v15, v30, v31
	ds_read_b128 v[28:31], v167 offset:432
	s_waitcnt lgkmcnt(3)
	v_max3_f32 v15, v15, v16, v17
	v_max3_f32 v15, v15, v18, v19
	ds_read_b128 v[16:19], v167 offset:448
	s_waitcnt lgkmcnt(3)
	v_max3_f32 v15, v15, v20, v21
	v_max3_f32 v15, v15, v22, v23
	ds_read_b128 v[20:23], v167 offset:464
	s_waitcnt lgkmcnt(3)
	v_max3_f32 v15, v15, v24, v25
	v_max3_f32 v15, v15, v26, v27
	ds_read_b128 v[24:27], v167 offset:480
	s_waitcnt lgkmcnt(3)
	v_max3_f32 v15, v15, v28, v29
	v_max3_f32 v15, v15, v30, v31
	ds_read_b128 v[28:31], v167 offset:496
	s_waitcnt lgkmcnt(3)
	v_max3_f32 v15, v15, v16, v17
	v_max3_f32 v15, v15, v18, v19
	s_waitcnt lgkmcnt(2)
	v_max3_f32 v15, v15, v20, v21
	v_max3_f32 v15, v15, v22, v23
	s_waitcnt lgkmcnt(1)
	v_max3_f32 v15, v15, v24, v25
	v_max3_f32 v15, v15, v26, v27
	s_waitcnt lgkmcnt(0)
	v_max3_f32 v15, v15, v28, v29
	v_max3_f32 v15, v15, v30, v31
	ds_write_b32 v171, v15 offset:32
